# gate-up seam: trailing half's re-offset barrier moved behind next-unit scheduling + accumulator zeroing via a flag SGPR (no code duplication)
# baseline (speedup 1.0000x reference)
.LBB0_629:
	s_mov_b64 s[40:41], 0x800
	s_and_b32 s3, s4, 3
	s_add_i32 m0, s66, 0x18000
	v_lshl_add_u64 v[6:7], v[6:7], 0, s[40:41]
	s_lshl_b32 s7, s6, 13
	s_lshl_b32 s74, s3, 5
	s_lshl_b32 s9, s3, 12
	s_waitcnt vmcnt(2)
	s_barrier
	global_load_lds_dwordx4 v[6:7], off
	v_lshl_add_u64 v[4:5], v[4:5], 0, s[40:41]
	s_add_i32 m0, s66, 0x1a000
	s_add_i32 s75, s66, 0x8000
	s_add_i32 s76, s66, 0xa000
	global_load_lds_dwordx4 v[4:5], off
	v_lshl_add_u64 v[2:3], v[2:3], 0, s[40:41]
	s_mov_b32 m0, s75
	s_add_u32 s4, s60, 0x100800
	global_load_lds_dwordx4 v[2:3], off
	v_lshl_add_u64 v[0:1], v[0:1], 0, s[40:41]
	s_mov_b32 m0, s76
	s_addc_u32 s5, s61, 0
	global_load_lds_dwordx4 v[0:1], off
	s_add_i32 m0, s66, 0x1c000
	v_lshl_add_u64 v[0:1], s[4:5], 0, v[162:163]
	global_load_lds_dwordx4 v[0:1], off
	v_lshl_add_u64 v[0:1], s[4:5], 0, v[166:167]
	s_add_i32 m0, s66, 0x1e000
	s_cmpk_lt_u32 s8, 0x100
	global_load_lds_dwordx4 v[0:1], off
	v_and_b32_e32 v0, 15, v8
	s_cselect_b64 s[42:43], -1, 0
	v_cmp_lt_u32_e32 vcc, 13, v0
	s_lshl_b32 s3, s3, 8
	s_and_b64 s[44:45], s[42:43], vcc
	s_ashr_i32 s77, s30, 31
	s_ashr_i32 s79, s2, 31
	s_add_u32 s46, s50, 0xac00
	s_addc_u32 s47, s51, 0
	v_lshrrev_b32_e32 v1, 1, v8
	s_add_u32 s48, s50, 0x15800
	v_and_b32_e32 v170, 24, v1
	v_lshlrev_b32_e32 v1, 6, v0
	v_lshlrev_b32_e32 v2, 2, v8
	s_addc_u32 s49, s51, 0
	s_add_i32 s3, s3, 0
	v_lshl_or_b32 v1, v170, 1, v1
	v_and_b32_e32 v2, 32, v2
	s_add_i32 s3, s3, 0x20400
	v_bitop3_b32 v3, v1, s7, v2 bitop3:0xde
	v_bitop3_b32 v171, v1, s9, v2 bitop3:0xde
	v_subrev_co_u32_e64 v1, s[4:5], 2, v0
	v_lshl_add_u32 v185, v170, 2, s3
	v_lshl_add_u32 v184, s6, 7, v1
	v_cmp_eq_u32_e64 s[6:7], 0, v0
	v_lshl_add_u32 v0, v0, 7, v185
	v_add_u32_e32 v186, 0xfffff900, v0
	v_add_u32_e32 v187, 0xfffff910, v0
	v_lshlrev_b32_e32 v0, 14, v9
	v_lshlrev_b32_e32 v1, 17, v10
	s_mov_b32 s3, 0xfff00000
	v_and_or_b32 v0, v0, s3, v1
	v_add_u32_e32 v0, v0, v11
	v_add3_u32 v168, v0, v12, v13
	v_lshlrev_b32_e32 v0, 14, v14
	v_lshlrev_b32_e32 v1, 17, v15
	v_and_or_b32 v0, v0, s3, v1
	s_waitcnt vmcnt(6)
	s_mov_b64 s[8:9], 0x80800
	v_add_u32_e32 v0, v0, v16
	v_lshl_add_u64 v[172:173], v[168:169], 0, s[8:9]
	v_add3_u32 v168, v0, v17, v18
	s_add_i32 s80, 0, 0x10000
	s_add_i32 s81, 0, 0x14000
	s_mov_b32 s78, s30
	v_lshl_add_u64 v[174:175], v[168:169], 0, s[8:9]
	v_mov_b64_e32 v[176:177], 0x15d6
	v_mov_b64_e32 v[178:179], 0x15d5
	v_add_u32_e32 v188, s80, v171
	v_add_u32_e32 v189, s81, v171
	v_add_u32_e32 v190, 0, v3
	v_mov_b32_e32 v191, 0x3727c5ac
	s_movk_i32 s82, 0x158
	s_movk_i32 s83, 0x3ff0
	s_movk_i32 s84, 0x3fe0
	s_movk_i32 s85, 0x3fd0
	s_movk_i32 s86, 0x3fc0
	s_movk_i32 s87, 0x3fb0
	s_movk_i32 s88, 0x3fa0
	s_movk_i32 s89, 0x3f90
	v_mov_b32_e32 v192, 0x3fff
	s_barrier
	s_mov_b32 s97, 0
	s_branch .LBB0_632

.LBB0_638:
	s_ashr_i32 s55, s54, 31
	s_lshl_b64 s[16:17], s[54:55], 21
	s_add_u32 s56, s22, s16
	s_addc_u32 s57, s23, s17
	s_and_b64 s[16:17], s[8:9], exec
	s_cselect_b32 s11, s57, s15
	s_cselect_b32 s13, s56, s14
	s_ashr_i32 s53, s52, 31
	s_lshl_b64 s[16:17], s[52:53], 21
	s_add_u32 s58, s68, s16
	s_addc_u32 s59, s69, s17
	s_and_b64 s[16:17], s[8:9], exec
	s_cselect_b32 s53, s59, s61
	s_cselect_b32 s55, s58, s60
	s_add_u32 s90, s60, 0x1000
	v_mov_b64_e32 v[0:1], 0
	v_mov_b64_e32 v[2:3], 0
	v_mov_b64_e32 v[4:5], 0
	v_mov_b64_e32 v[6:7], 0
	v_mov_b64_e32 v[8:9], 0
	v_mov_b64_e32 v[10:11], 0
	v_mov_b64_e32 v[12:13], 0
	v_mov_b64_e32 v[14:15], 0
	v_mov_b64_e32 v[16:17], 0
	v_mov_b64_e32 v[18:19], 0
	v_mov_b64_e32 v[20:21], 0
	v_mov_b64_e32 v[22:23], 0
	v_mov_b64_e32 v[24:25], 0
	v_mov_b64_e32 v[26:27], 0
	v_mov_b64_e32 v[28:29], 0
	v_mov_b64_e32 v[30:31], 0
	v_mov_b64_e32 v[32:33], 0
	v_mov_b64_e32 v[34:35], 0
	v_mov_b64_e32 v[36:37], 0
	v_mov_b64_e32 v[38:39], 0
	v_mov_b64_e32 v[40:41], 0
	v_mov_b64_e32 v[42:43], 0
	v_mov_b64_e32 v[44:45], 0
	v_mov_b64_e32 v[46:47], 0
	v_mov_b64_e32 v[48:49], 0
	v_mov_b64_e32 v[50:51], 0
	v_mov_b64_e32 v[68:69], 0
	v_mov_b64_e32 v[70:71], 0
	v_mov_b64_e32 v[88:89], 0
	v_mov_b64_e32 v[90:91], 0
	v_mov_b64_e32 v[92:93], 0
	v_mov_b64_e32 v[94:95], 0
	v_mov_b64_e32 v[96:97], 0
	v_mov_b64_e32 v[98:99], 0
	v_mov_b64_e32 v[100:101], 0
	v_mov_b64_e32 v[102:103], 0
	v_mov_b64_e32 v[104:105], 0
	v_mov_b64_e32 v[106:107], 0
	v_mov_b64_e32 v[108:109], 0
	v_mov_b64_e32 v[110:111], 0
	v_mov_b64_e32 v[112:113], 0
	v_mov_b64_e32 v[114:115], 0
	v_mov_b64_e32 v[116:117], 0
	v_mov_b64_e32 v[118:119], 0
	v_mov_b64_e32 v[120:121], 0
	v_mov_b64_e32 v[122:123], 0
	v_mov_b64_e32 v[124:125], 0
	v_mov_b64_e32 v[126:127], 0
	v_mov_b64_e32 v[128:129], 0
	v_mov_b64_e32 v[130:131], 0
	v_mov_b64_e32 v[132:133], 0
	v_mov_b64_e32 v[134:135], 0
	v_mov_b64_e32 v[136:137], 0
	v_mov_b64_e32 v[138:139], 0
	v_mov_b64_e32 v[140:141], 0
	v_mov_b64_e32 v[142:143], 0
	v_mov_b64_e32 v[144:145], 0
	v_mov_b64_e32 v[146:147], 0
	v_mov_b64_e32 v[148:149], 0
	v_mov_b64_e32 v[150:151], 0
	v_mov_b64_e32 v[152:153], 0
	v_mov_b64_e32 v[154:155], 0
	v_mov_b64_e32 v[156:157], 0
	v_mov_b64_e32 v[158:159], 0
	s_addc_u32 s91, s61, 0
	s_mov_b32 s93, -2
	s_cmp_eq_u32 s97, 0
	s_cbranch_scc1 .Lhb_skip
	s_mov_b32 s97, 0
	s_barrier
.Lhb_skip:
.LBB0_639:
	s_add_i32 m0, s66, 0xc000
	ds_read_b128 v[52:55], v188
	ds_read_b128 v[56:59], v188 offset:1024
	ds_read_b128 v[60:63], v188 offset:2048
	ds_read_b128 v[64:67], v188 offset:3072
	ds_read_b128 v[72:75], v189
	ds_read_b128 v[76:79], v189 offset:1024
	ds_read_b128 v[80:83], v189 offset:2048
	ds_read_b128 v[84:87], v189 offset:3072
	s_add_u32 s60, s14, 0x1000
	s_addc_u32 s61, s15, 0
	s_cmp_eq_u32 s93, 60
	s_cselect_b32 s65, s11, s61
	s_cselect_b32 s64, s13, s60
	s_cselect_b32 s63, s53, s91
	s_cselect_b32 s62, s55, s90
	s_cbranch_scc0 .Lpf_skip
	v_mbcnt_lo_u32_b32 v224, -1, 0
	v_mbcnt_hi_u32_b32 v224, -1, v224
	s_cmp_lt_u32 s19, 0x800
	s_cbranch_scc0 .Lpf_ss
	v_and_b32_e32 v224, 31, v224
	v_lshlrev_b32_e32 v224, 4, v224
	s_lshl_b32 s3, s10, 9
	v_add_u32_e32 v224, s3, v224
	s_add_i32 m0, s19, 0x21000
	s_cmp_eq_u32 s19, 0
	s_cbranch_scc0 .Lpf_w1
	s_mov_b32 exec_lo, -1
	s_mov_b32 exec_hi, 0
	global_load_lds_dwordx4 v224, s[50:51]
	s_mov_b32 exec_lo, 0
	s_mov_b32 exec_hi, -1
	global_load_lds_dwordx4 v224, s[46:47]
	s_mov_b32 exec_lo, -1
	s_branch .Lpf_skip

.LBB0_677:
	s_or_b64 exec, exec, s[62:63]
	s_andn2_b64 vcc, exec, s[8:9]
	s_mov_b64 s[8:9], -1
	s_cbranch_vccnz .LBB0_631
	s_and_b64 vcc, exec, s[10:11]
	s_cbranch_vccnz .LBB0_630
	s_mov_b32 s97, 1
	s_branch .LBB0_630
